# selected-branch P.V: all V-fragment LDS reads of a key block hoisted before its exps into free VGPRs (v184-v235), MFMAs back to back
# speedup vs baseline: 1.0101x; 1.0031x over previous
.LBB0_762:
	v_add3_u32 v184, s75, v167, v168
	v_lshl_add_u32 v185, v169, 1, v184
	v_lshl_add_u32 v186, v170, 1, v184
	v_lshl_add_u32 v187, v171, 1, v184
	v_lshl_add_u32 v184, v172, 1, v184
	ds_read_b64 v[188:189], v185 offset:8192
	ds_read_b64 v[190:191], v186 offset:8192
	ds_read_b64 v[192:193], v185 offset:10240
	ds_read_b64 v[194:195], v186 offset:10240
	ds_read_b64 v[196:197], v185 offset:12288
	ds_read_b64 v[198:199], v186 offset:12288
	ds_read_b64 v[200:201], v185 offset:14336
	ds_read_b64 v[202:203], v186 offset:14336
	ds_read_b64 v[204:205], v187 offset:8192
	ds_read_b64 v[206:207], v184 offset:8192
	ds_read_b64 v[208:209], v187 offset:10240
	ds_read_b64 v[210:211], v184 offset:10240
	ds_read_b64 v[212:213], v187 offset:12288
	ds_read_b64 v[214:215], v184 offset:12288
	ds_read_b64 v[216:217], v187 offset:14336
	ds_read_b64 v[218:219], v184 offset:14336
	v_exp_f32_e32 v2, v120
	v_exp_f32_e32 v3, v121
	v_exp_f32_e32 v112, v112
	v_exp_f32_e32 v113, v113
	v_exp_f32_e32 v120, v122
	v_exp_f32_e32 v121, v123
	v_exp_f32_e32 v122, v132
	v_exp_f32_e32 v123, v133
	v_exp_f32_e32 v132, v134
	v_exp_f32_e32 v133, v135
	v_exp_f32_e32 v116, v116
	v_exp_f32_e32 v117, v117
	v_exp_f32_e32 v118, v118
	v_exp_f32_e32 v119, v119
	v_exp_f32_e32 v134, v114
	v_exp_f32_e32 v135, v115
	v_exp_f32_e32 v140, v140
	v_exp_f32_e32 v141, v141
	v_exp_f32_e32 v142, v142
	v_exp_f32_e32 v143, v143
	v_exp_f32_e32 v136, v136
	v_exp_f32_e32 v137, v137
	v_exp_f32_e32 v138, v138
	v_exp_f32_e32 v139, v139
	v_exp_f32_e32 v155, v124
	v_exp_f32_e32 v177, v125
	v_exp_f32_e32 v178, v126
	v_exp_f32_e32 v179, v127
	v_exp_f32_e32 v180, v128
	v_exp_f32_e32 v181, v129
	v_exp_f32_e32 v182, v130
	v_exp_f32_e32 v183, v131
	v_cvt_pk_bf16_f32 v114, v2, v3
	v_cvt_pk_bf16_f32 v115, v120, v121
	v_cvt_pk_bf16_f32 v120, v112, v113
	v_cvt_pk_bf16_f32 v116, v116, v117
	v_cvt_pk_bf16_f32 v117, v118, v119
	v_cvt_pk_bf16_f32 v118, v122, v123
	v_cvt_pk_bf16_f32 v119, v132, v133
	v_cvt_pk_bf16_f32 v121, v134, v135
	s_andn2_b64 vcc, exec, s[34:35]
	s_waitcnt lgkmcnt(0)
	s_nop 0
	v_mfma_f32_16x16x32_bf16 v[52:55], v[188:191], v[114:117], v[52:55]
	v_mfma_f32_16x16x32_bf16 v[40:43], v[188:191], v[118:121], v[40:43]
	v_mfma_f32_16x16x32_bf16 v[48:51], v[192:195], v[114:117], v[48:51]
	v_mfma_f32_16x16x32_bf16 v[32:35], v[192:195], v[118:121], v[32:35]
	v_mfma_f32_16x16x32_bf16 v[44:47], v[196:199], v[114:117], v[44:47]
	v_mfma_f32_16x16x32_bf16 v[28:31], v[196:199], v[118:121], v[28:31]
	v_mfma_f32_16x16x32_bf16 v[36:39], v[200:203], v[114:117], v[36:39]
	v_mfma_f32_16x16x32_bf16 v[24:27], v[200:203], v[118:121], v[24:27]
	v_mfma_f32_16x16x32_bf16 v[72:75], v[20:23], v[114:117], v[72:75]
	v_cvt_pk_bf16_f32 v114, v140, v141
	v_cvt_pk_bf16_f32 v115, v142, v143
	v_cvt_pk_bf16_f32 v116, v155, v177
	v_mfma_f32_16x16x32_bf16 v[76:79], v[20:23], v[118:121], v[76:79]
	v_cvt_pk_bf16_f32 v117, v178, v179
	v_cvt_pk_bf16_f32 v118, v136, v137
	v_cvt_pk_bf16_f32 v119, v138, v139
	v_cvt_pk_bf16_f32 v120, v180, v181
	v_cvt_pk_bf16_f32 v121, v182, v183
	s_nop 1
	v_mfma_f32_16x16x32_bf16 v[52:55], v[204:207], v[114:117], v[52:55]
	v_mfma_f32_16x16x32_bf16 v[40:43], v[204:207], v[118:121], v[40:43]
	v_mfma_f32_16x16x32_bf16 v[48:51], v[208:211], v[114:117], v[48:51]
	v_mfma_f32_16x16x32_bf16 v[32:35], v[208:211], v[118:121], v[32:35]
	v_mfma_f32_16x16x32_bf16 v[72:75], v[20:23], v[114:117], v[72:75]
	v_mfma_f32_16x16x32_bf16 v[76:79], v[20:23], v[118:121], v[76:79]
	v_mfma_f32_16x16x32_bf16 v[44:47], v[212:215], v[114:117], v[44:47]
	v_mfma_f32_16x16x32_bf16 v[28:31], v[212:215], v[118:121], v[28:31]
	v_mfma_f32_16x16x32_bf16 v[36:39], v[216:219], v[114:117], v[36:39]
	v_mfma_f32_16x16x32_bf16 v[24:27], v[216:219], v[118:121], v[24:27]
	s_cbranch_vccnz .LBB0_764
	ds_read_b64 v[220:221], v185 offset:24576
	ds_read_b64 v[222:223], v186 offset:24576
	ds_read_b64 v[224:225], v185 offset:26624
	ds_read_b64 v[226:227], v186 offset:26624
	ds_read_b64 v[228:229], v185 offset:28672
	ds_read_b64 v[230:231], v186 offset:28672
	ds_read_b64 v[232:233], v185 offset:30720
	ds_read_b64 v[234:235], v186 offset:30720
	ds_read_b64 v[188:189], v187 offset:24576
	ds_read_b64 v[190:191], v184 offset:24576
	ds_read_b64 v[192:193], v187 offset:26624
	ds_read_b64 v[194:195], v184 offset:26624
	ds_read_b64 v[196:197], v187 offset:28672
	ds_read_b64 v[198:199], v184 offset:28672
	ds_read_b64 v[200:201], v187 offset:30720
	ds_read_b64 v[202:203], v184 offset:30720
	v_exp_f32_e32 v88, v88
	v_exp_f32_e32 v89, v89
	v_exp_f32_e32 v90, v90
	v_exp_f32_e32 v91, v91
	v_exp_f32_e32 v100, v100
	v_exp_f32_e32 v101, v101
	v_exp_f32_e32 v102, v102
	v_exp_f32_e32 v103, v103
	v_exp_f32_e32 v84, v84
	v_exp_f32_e32 v85, v85
	v_exp_f32_e32 v86, v86
	v_exp_f32_e32 v87, v87
	v_exp_f32_e32 v80, v80
	v_exp_f32_e32 v81, v81
	v_exp_f32_e32 v82, v82
	v_exp_f32_e32 v83, v83
	v_cvt_pk_bf16_f32 v114, v88, v89
	v_cvt_pk_bf16_f32 v115, v90, v91
	v_cvt_pk_bf16_f32 v116, v84, v85
	v_cvt_pk_bf16_f32 v117, v86, v87
	v_cvt_pk_bf16_f32 v118, v100, v101
	v_cvt_pk_bf16_f32 v119, v102, v103
	v_cvt_pk_bf16_f32 v120, v80, v81
	v_cvt_pk_bf16_f32 v121, v82, v83
	s_waitcnt lgkmcnt(0)
	s_nop 0
	v_mfma_f32_16x16x32_bf16 v[52:55], v[220:223], v[114:117], v[52:55]
	v_mfma_f32_16x16x32_bf16 v[40:43], v[220:223], v[118:121], v[40:43]
	v_exp_f32_e32 v108, v108
	v_exp_f32_e32 v109, v109
	v_mfma_f32_16x16x32_bf16 v[76:79], v[20:23], v[118:121], v[76:79]
	v_exp_f32_e32 v110, v110
	v_exp_f32_e32 v111, v111
	v_exp_f32_e32 v104, v104
	v_mfma_f32_16x16x32_bf16 v[48:51], v[224:227], v[114:117], v[48:51]
	v_exp_f32_e32 v105, v105
	v_exp_f32_e32 v106, v106
	v_exp_f32_e32 v107, v107
	v_mfma_f32_16x16x32_bf16 v[32:35], v[224:227], v[118:121], v[32:35]
	v_exp_f32_e32 v92, v92
	v_exp_f32_e32 v93, v93
	v_mfma_f32_16x16x32_bf16 v[28:31], v[228:231], v[118:121], v[28:31]
	v_exp_f32_e32 v94, v94
	v_exp_f32_e32 v95, v95
	v_exp_f32_e32 v96, v96
	v_mfma_f32_16x16x32_bf16 v[24:27], v[232:235], v[118:121], v[24:27]
	v_exp_f32_e32 v97, v97
	v_exp_f32_e32 v98, v98
	v_mfma_f32_16x16x32_bf16 v[36:39], v[232:235], v[114:117], v[36:39]
	v_exp_f32_e32 v99, v99
	v_mfma_f32_16x16x32_bf16 v[72:75], v[20:23], v[114:117], v[72:75]
	v_cvt_pk_bf16_f32 v112, v108, v109
	v_cvt_pk_bf16_f32 v113, v110, v111
	v_cvt_pk_bf16_f32 v118, v96, v97
	v_mfma_f32_16x16x32_bf16 v[44:47], v[228:231], v[114:117], v[44:47]
	v_cvt_pk_bf16_f32 v114, v92, v93
	v_cvt_pk_bf16_f32 v115, v94, v95
	v_cvt_pk_bf16_f32 v116, v104, v105
	v_cvt_pk_bf16_f32 v117, v106, v107
	v_cvt_pk_bf16_f32 v119, v98, v99
	s_nop 1
	v_mfma_f32_16x16x32_bf16 v[52:55], v[188:191], v[112:115], v[52:55]
	v_mfma_f32_16x16x32_bf16 v[40:43], v[188:191], v[116:119], v[40:43]
	v_mfma_f32_16x16x32_bf16 v[48:51], v[192:195], v[112:115], v[48:51]
	v_mfma_f32_16x16x32_bf16 v[32:35], v[192:195], v[116:119], v[32:35]
	v_mfma_f32_16x16x32_bf16 v[72:75], v[20:23], v[112:115], v[72:75]
	v_mfma_f32_16x16x32_bf16 v[76:79], v[20:23], v[116:119], v[76:79]
	v_mfma_f32_16x16x32_bf16 v[44:47], v[196:199], v[112:115], v[44:47]
	v_mfma_f32_16x16x32_bf16 v[28:31], v[196:199], v[116:119], v[28:31]
	v_mfma_f32_16x16x32_bf16 v[36:39], v[200:203], v[112:115], v[36:39]
	v_mfma_f32_16x16x32_bf16 v[24:27], v[200:203], v[116:119], v[24:27]
